# MLA fast128 compute block hand-scheduled: S/exp/PV software-pipelined across 32-key sub-blocks, 5-buffer LDS fragment ring with counted lgkmcnt
# speedup vs baseline: 1.0249x; 1.0249x over previous
.LBB0_1483:
	s_add_i32 s53, s53, 1
	ds_read_b128 v[212:215], v165
	ds_read_b128 v[216:219], v165 offset:64
	ds_read_b128 v[220:223], v165 offset:128
	ds_read_b128 v[224:227], v165 offset:3328
	ds_read_b128 v[228:231], v165 offset:3392
	v_add_u32_e32 v248, 0x6800, v160
	v_add_u32_e32 v249, 0x7900, v160
	v_add_u32_e32 v188, 0x8a00, v160
	v_add_u32_e32 v211, 0x9b00, v160
	v_add_u32_e32 v166, 0xac00, v160
	s_waitcnt lgkmcnt(4)
	v_mfma_f32_16x16x32_bf16 v[232:235], v[212:215], v[0:3], 0
	v_mfma_f32_16x16x32_bf16 v[240:243], v[212:215], v[12:15], 0
	ds_read_b128 v[212:215], v165 offset:3456
	s_waitcnt lgkmcnt(4)
	v_mfma_f32_16x16x32_bf16 v[232:235], v[216:219], v[4:7], v[232:235]
	v_mfma_f32_16x16x32_bf16 v[240:243], v[216:219], v[16:19], v[240:243]
	ds_read_b128 v[216:219], v165 offset:6656
	s_waitcnt lgkmcnt(4)
	v_mfma_f32_16x16x32_bf16 v[232:235], v[220:223], v[8:11], v[232:235]
	v_mfma_f32_16x16x32_bf16 v[240:243], v[220:223], v[20:23], v[240:243]
	ds_read_b128 v[220:223], v165 offset:6720
	s_waitcnt lgkmcnt(4)
	v_mfma_f32_16x16x32_bf16 v[236:239], v[224:227], v[0:3], 0
	v_mfma_f32_16x16x32_bf16 v[244:247], v[224:227], v[12:15], 0
	ds_read_b128 v[224:227], v165 offset:6784
	s_waitcnt lgkmcnt(4)
	v_mfma_f32_16x16x32_bf16 v[236:239], v[228:231], v[4:7], v[236:239]
	v_mfma_f32_16x16x32_bf16 v[244:247], v[228:231], v[16:19], v[244:247]
	v_exp_f32_e32 v232, v232
	ds_read_b128 v[228:231], v165 offset:9984
	s_waitcnt lgkmcnt(4)
	v_mfma_f32_16x16x32_bf16 v[236:239], v[212:215], v[8:11], v[236:239]
	v_exp_f32_e32 v233, v233
	v_mfma_f32_16x16x32_bf16 v[244:247], v[212:215], v[20:23], v[244:247]
	v_exp_f32_e32 v234, v234
	ds_read_b128 v[212:215], v165 offset:10048
	s_waitcnt lgkmcnt(4)
	v_mfma_f32_16x16x32_bf16 v[168:171], v[216:219], v[0:3], 0
	v_exp_f32_e32 v235, v235
	v_mfma_f32_16x16x32_bf16 v[176:179], v[216:219], v[12:15], 0
	v_cvt_pk_bf16_f32 v232, v232, v233
	v_cvt_pk_bf16_f32 v233, v234, v235
	ds_read_b128 v[216:219], v165 offset:10112
	s_waitcnt lgkmcnt(4)
	v_mfma_f32_16x16x32_bf16 v[168:171], v[220:223], v[4:7], v[168:171]
	v_exp_f32_e32 v240, v240
	v_mfma_f32_16x16x32_bf16 v[176:179], v[220:223], v[16:19], v[176:179]
	v_exp_f32_e32 v241, v241
	ds_read2_b64 v[220:223], v248 offset1:4
	s_waitcnt lgkmcnt(4)
	v_mfma_f32_16x16x32_bf16 v[168:171], v[224:227], v[8:11], v[168:171]
	v_exp_f32_e32 v242, v242
	v_mfma_f32_16x16x32_bf16 v[176:179], v[224:227], v[20:23], v[176:179]
	v_exp_f32_e32 v243, v243
	ds_read2_b64 v[224:227], v249 offset1:4
	s_waitcnt lgkmcnt(4)
	v_mfma_f32_16x16x32_bf16 v[172:175], v[228:231], v[0:3], 0
	v_cvt_pk_bf16_f32 v240, v240, v241
	v_cvt_pk_bf16_f32 v241, v242, v243
	v_mfma_f32_16x16x32_bf16 v[108:111], v[228:231], v[12:15], 0
	v_exp_f32_e32 v236, v236
	ds_read2_b64 v[228:231], v188 offset1:4
	s_waitcnt lgkmcnt(4)
	v_mfma_f32_16x16x32_bf16 v[172:175], v[212:215], v[4:7], v[172:175]
	v_exp_f32_e32 v237, v237
	v_mfma_f32_16x16x32_bf16 v[108:111], v[212:215], v[16:19], v[108:111]
	v_exp_f32_e32 v238, v238
	ds_read2_b64 v[212:215], v211 offset1:4
	s_waitcnt lgkmcnt(4)
	v_mfma_f32_16x16x32_bf16 v[172:175], v[216:219], v[8:11], v[172:175]
	v_exp_f32_e32 v239, v239
	v_mfma_f32_16x16x32_bf16 v[108:111], v[216:219], v[20:23], v[108:111]
	v_cvt_pk_bf16_f32 v234, v236, v237
	v_cvt_pk_bf16_f32 v235, v238, v239
	ds_read2_b64 v[216:219], v166 offset1:4
	s_waitcnt lgkmcnt(4)
	v_mfma_f32_16x16x32_bf16 v[84:87], v[220:223], v[232:235], v[84:87]
	v_exp_f32_e32 v244, v244
	v_exp_f32_e32 v245, v245
	v_exp_f32_e32 v246, v246
	v_exp_f32_e32 v247, v247
	v_cvt_pk_bf16_f32 v242, v244, v245
	v_cvt_pk_bf16_f32 v243, v246, v247
	v_exp_f32_e32 v168, v168
	v_exp_f32_e32 v169, v169
	v_mfma_f32_16x16x32_bf16 v[68:71], v[220:223], v[240:243], v[68:71]
	v_exp_f32_e32 v170, v170
	ds_read_b128 v[220:223], v165 offset:13312
	s_waitcnt lgkmcnt(4)
	v_mfma_f32_16x16x32_bf16 v[88:91], v[224:227], v[232:235], v[88:91]
	v_exp_f32_e32 v171, v171
	v_mfma_f32_16x16x32_bf16 v[72:75], v[224:227], v[240:243], v[72:75]
	v_cvt_pk_bf16_f32 v168, v168, v169
	v_cvt_pk_bf16_f32 v169, v170, v171
	ds_read_b128 v[224:227], v165 offset:13376
	s_waitcnt lgkmcnt(4)
	v_mfma_f32_16x16x32_bf16 v[92:95], v[228:231], v[232:235], v[92:95]
	v_exp_f32_e32 v176, v176
	v_mfma_f32_16x16x32_bf16 v[76:79], v[228:231], v[240:243], v[76:79]
	v_exp_f32_e32 v177, v177
	ds_read_b128 v[228:231], v165 offset:13440
	s_waitcnt lgkmcnt(4)
	v_mfma_f32_16x16x32_bf16 v[96:99], v[212:215], v[232:235], v[96:99]
	v_exp_f32_e32 v178, v178
	v_mfma_f32_16x16x32_bf16 v[80:83], v[212:215], v[240:243], v[80:83]
	v_exp_f32_e32 v179, v179
	ds_read_b128 v[212:215], v165 offset:16640
	s_waitcnt lgkmcnt(4)
	v_mfma_f32_16x16x32_bf16 v[104:107], v[216:219], v[232:235], v[104:107]
	v_cvt_pk_bf16_f32 v176, v176, v177
	v_cvt_pk_bf16_f32 v177, v178, v179
	v_mfma_f32_16x16x32_bf16 v[100:103], v[216:219], v[240:243], v[100:103]
	v_exp_f32_e32 v172, v172
	ds_read_b128 v[216:219], v165 offset:16704
	s_waitcnt lgkmcnt(4)
	v_mfma_f32_16x16x32_bf16 v[232:235], v[220:223], v[0:3], 0
	v_exp_f32_e32 v173, v173
	v_mfma_f32_16x16x32_bf16 v[240:243], v[220:223], v[12:15], 0
	v_exp_f32_e32 v174, v174
	ds_read_b128 v[220:223], v165 offset:16768
	s_waitcnt lgkmcnt(4)
	v_mfma_f32_16x16x32_bf16 v[232:235], v[224:227], v[4:7], v[232:235]
	v_exp_f32_e32 v175, v175
	v_mfma_f32_16x16x32_bf16 v[240:243], v[224:227], v[16:19], v[240:243]
	v_cvt_pk_bf16_f32 v170, v172, v173
	v_cvt_pk_bf16_f32 v171, v174, v175
	ds_read2_b64 v[224:227], v248 offset0:8 offset1:12
	s_waitcnt lgkmcnt(4)
	v_mfma_f32_16x16x32_bf16 v[232:235], v[228:231], v[8:11], v[232:235]
	v_exp_f32_e32 v108, v108
	v_mfma_f32_16x16x32_bf16 v[240:243], v[228:231], v[20:23], v[240:243]
	v_exp_f32_e32 v109, v109
	ds_read2_b64 v[228:231], v249 offset0:8 offset1:12
	s_waitcnt lgkmcnt(4)
	v_mfma_f32_16x16x32_bf16 v[236:239], v[212:215], v[0:3], 0
	v_exp_f32_e32 v110, v110
	v_mfma_f32_16x16x32_bf16 v[244:247], v[212:215], v[12:15], 0
	v_exp_f32_e32 v111, v111
	ds_read2_b64 v[212:215], v188 offset0:8 offset1:12
	s_waitcnt lgkmcnt(4)
	v_mfma_f32_16x16x32_bf16 v[236:239], v[216:219], v[4:7], v[236:239]
	v_cvt_pk_bf16_f32 v178, v108, v109
	v_cvt_pk_bf16_f32 v179, v110, v111
	v_mfma_f32_16x16x32_bf16 v[244:247], v[216:219], v[16:19], v[244:247]
	v_exp_f32_e32 v232, v232
	ds_read2_b64 v[216:219], v211 offset0:8 offset1:12
	s_waitcnt lgkmcnt(4)
	v_mfma_f32_16x16x32_bf16 v[236:239], v[220:223], v[8:11], v[236:239]
	v_exp_f32_e32 v233, v233
	v_mfma_f32_16x16x32_bf16 v[244:247], v[220:223], v[20:23], v[244:247]
	v_exp_f32_e32 v234, v234
	ds_read2_b64 v[220:223], v166 offset0:8 offset1:12
	s_waitcnt lgkmcnt(4)
	v_mfma_f32_16x16x32_bf16 v[84:87], v[224:227], v[168:171], v[84:87]
	v_exp_f32_e32 v235, v235
	v_mfma_f32_16x16x32_bf16 v[68:71], v[224:227], v[176:179], v[68:71]
	v_cvt_pk_bf16_f32 v232, v232, v233
	v_cvt_pk_bf16_f32 v233, v234, v235
	ds_read_b128 v[224:227], v165 offset:19968
	s_waitcnt lgkmcnt(4)
	v_mfma_f32_16x16x32_bf16 v[88:91], v[228:231], v[168:171], v[88:91]
	v_exp_f32_e32 v240, v240
	v_mfma_f32_16x16x32_bf16 v[72:75], v[228:231], v[176:179], v[72:75]
	v_exp_f32_e32 v241, v241
	ds_read_b128 v[228:231], v165 offset:20032
	s_waitcnt lgkmcnt(4)
	v_mfma_f32_16x16x32_bf16 v[92:95], v[212:215], v[168:171], v[92:95]
	v_exp_f32_e32 v242, v242
	v_mfma_f32_16x16x32_bf16 v[76:79], v[212:215], v[176:179], v[76:79]
	v_exp_f32_e32 v243, v243
	ds_read_b128 v[212:215], v165 offset:20096
	s_waitcnt lgkmcnt(4)
	v_mfma_f32_16x16x32_bf16 v[96:99], v[216:219], v[168:171], v[96:99]
	v_cvt_pk_bf16_f32 v240, v240, v241
	v_cvt_pk_bf16_f32 v241, v242, v243
	v_mfma_f32_16x16x32_bf16 v[80:83], v[216:219], v[176:179], v[80:83]
	v_exp_f32_e32 v236, v236
	ds_read_b128 v[216:219], v165 offset:23296
	s_waitcnt lgkmcnt(4)
	v_mfma_f32_16x16x32_bf16 v[104:107], v[220:223], v[168:171], v[104:107]
	v_exp_f32_e32 v237, v237
	v_mfma_f32_16x16x32_bf16 v[100:103], v[220:223], v[176:179], v[100:103]
	v_exp_f32_e32 v238, v238
	ds_read_b128 v[220:223], v165 offset:23360
	s_waitcnt lgkmcnt(4)
	v_mfma_f32_16x16x32_bf16 v[168:171], v[224:227], v[0:3], 0
	v_exp_f32_e32 v239, v239
	v_mfma_f32_16x16x32_bf16 v[176:179], v[224:227], v[12:15], 0
	v_cvt_pk_bf16_f32 v234, v236, v237
	v_cvt_pk_bf16_f32 v235, v238, v239
	ds_read_b128 v[224:227], v165 offset:23424
	s_waitcnt lgkmcnt(4)
	v_mfma_f32_16x16x32_bf16 v[168:171], v[228:231], v[4:7], v[168:171]
	v_exp_f32_e32 v244, v244
	v_mfma_f32_16x16x32_bf16 v[176:179], v[228:231], v[16:19], v[176:179]
	v_exp_f32_e32 v245, v245
	ds_read2_b64 v[228:231], v248 offset0:16 offset1:20
	s_waitcnt lgkmcnt(4)
	v_mfma_f32_16x16x32_bf16 v[168:171], v[212:215], v[8:11], v[168:171]
	v_exp_f32_e32 v246, v246
	v_mfma_f32_16x16x32_bf16 v[176:179], v[212:215], v[20:23], v[176:179]
	v_exp_f32_e32 v247, v247
	ds_read2_b64 v[212:215], v249 offset0:16 offset1:20
	s_waitcnt lgkmcnt(4)
	v_mfma_f32_16x16x32_bf16 v[172:175], v[216:219], v[0:3], 0
	v_cvt_pk_bf16_f32 v242, v244, v245
	v_cvt_pk_bf16_f32 v243, v246, v247
	v_mfma_f32_16x16x32_bf16 v[108:111], v[216:219], v[12:15], 0
	v_exp_f32_e32 v168, v168
	ds_read2_b64 v[216:219], v188 offset0:16 offset1:20
	s_waitcnt lgkmcnt(4)
	v_mfma_f32_16x16x32_bf16 v[172:175], v[220:223], v[4:7], v[172:175]
	v_exp_f32_e32 v169, v169
	v_mfma_f32_16x16x32_bf16 v[108:111], v[220:223], v[16:19], v[108:111]
	v_exp_f32_e32 v170, v170
	ds_read2_b64 v[220:223], v211 offset0:16 offset1:20
	s_waitcnt lgkmcnt(4)
	v_mfma_f32_16x16x32_bf16 v[172:175], v[224:227], v[8:11], v[172:175]
	v_exp_f32_e32 v171, v171
	v_mfma_f32_16x16x32_bf16 v[108:111], v[224:227], v[20:23], v[108:111]
	v_cvt_pk_bf16_f32 v168, v168, v169
	v_cvt_pk_bf16_f32 v169, v170, v171
	ds_read2_b64 v[224:227], v166 offset0:16 offset1:20
	s_waitcnt lgkmcnt(4)
	v_mfma_f32_16x16x32_bf16 v[84:87], v[228:231], v[232:235], v[84:87]
	v_exp_f32_e32 v176, v176
	v_mfma_f32_16x16x32_bf16 v[68:71], v[228:231], v[240:243], v[68:71]
	v_exp_f32_e32 v177, v177
	ds_read2_b64 v[228:231], v248 offset0:24 offset1:28
	s_waitcnt lgkmcnt(4)
	v_mfma_f32_16x16x32_bf16 v[88:91], v[212:215], v[232:235], v[88:91]
	v_exp_f32_e32 v178, v178
	v_mfma_f32_16x16x32_bf16 v[72:75], v[212:215], v[240:243], v[72:75]
	v_exp_f32_e32 v179, v179
	ds_read2_b64 v[212:215], v249 offset0:24 offset1:28
	s_waitcnt lgkmcnt(4)
	v_mfma_f32_16x16x32_bf16 v[92:95], v[216:219], v[232:235], v[92:95]
	v_cvt_pk_bf16_f32 v176, v176, v177
	v_cvt_pk_bf16_f32 v177, v178, v179
	v_mfma_f32_16x16x32_bf16 v[76:79], v[216:219], v[240:243], v[76:79]
	v_exp_f32_e32 v172, v172
	ds_read2_b64 v[216:219], v188 offset0:24 offset1:28
	s_waitcnt lgkmcnt(4)
	v_mfma_f32_16x16x32_bf16 v[96:99], v[220:223], v[232:235], v[96:99]
	v_exp_f32_e32 v173, v173
	v_mfma_f32_16x16x32_bf16 v[80:83], v[220:223], v[240:243], v[80:83]
	v_exp_f32_e32 v174, v174
	ds_read2_b64 v[220:223], v211 offset0:24 offset1:28
	s_waitcnt lgkmcnt(4)
	v_mfma_f32_16x16x32_bf16 v[104:107], v[224:227], v[232:235], v[104:107]
	v_exp_f32_e32 v175, v175
	v_mfma_f32_16x16x32_bf16 v[100:103], v[224:227], v[240:243], v[100:103]
	v_cvt_pk_bf16_f32 v170, v172, v173
	v_cvt_pk_bf16_f32 v171, v174, v175
	ds_read2_b64 v[224:227], v166 offset0:24 offset1:28
	s_waitcnt lgkmcnt(4)
	v_mfma_f32_16x16x32_bf16 v[84:87], v[228:231], v[168:171], v[84:87]
	v_exp_f32_e32 v108, v108
	s_waitcnt lgkmcnt(3)
	v_mfma_f32_16x16x32_bf16 v[88:91], v[212:215], v[168:171], v[88:91]
	v_exp_f32_e32 v109, v109
	s_waitcnt lgkmcnt(2)
	v_mfma_f32_16x16x32_bf16 v[92:95], v[216:219], v[168:171], v[92:95]
	v_exp_f32_e32 v110, v110
	s_waitcnt lgkmcnt(1)
	v_mfma_f32_16x16x32_bf16 v[96:99], v[220:223], v[168:171], v[96:99]
	v_exp_f32_e32 v111, v111
	s_waitcnt lgkmcnt(0)
	v_mfma_f32_16x16x32_bf16 v[104:107], v[224:227], v[168:171], v[104:107]
	v_cvt_pk_bf16_f32 v178, v108, v109
	v_cvt_pk_bf16_f32 v179, v110, v111
	s_nop 0
	s_nop 0
	v_mfma_f32_16x16x32_bf16 v[68:71], v[228:231], v[176:179], v[68:71]
	v_mfma_f32_16x16x32_bf16 v[72:75], v[212:215], v[176:179], v[72:75]
	v_mfma_f32_16x16x32_bf16 v[76:79], v[216:219], v[176:179], v[76:79]
	v_mfma_f32_16x16x32_bf16 v[80:83], v[220:223], v[176:179], v[80:83]
	v_mfma_f32_16x16x32_bf16 v[100:103], v[224:227], v[176:179], v[100:103]
	s_cmp_eq_u32 s53, 34
	s_cbranch_scc1 .LBB0_1504
